# as v167 plus the RMS row-sum exchange goes through L2 (plain slot store, sc0 slot loads) when the panel's eight writers are proven to share the poller's XCD (flag from the P4a->P4b panel counter, ever
# baseline (speedup 1.0000x reference)
.LBB0_1029:
	v_and_b32_e32 v142, 15, v56
	v_bfe_u32 v143, v56, 4, 2
	v_or_b32_e32 v63, s16, v142
	v_lshlrev_b32_e32 v80, 4, v143
	v_lshlrev_b32_e32 v81, 6, v63
	s_movk_i32 s26, 0x3c0
	v_lshlrev_b32_e32 v63, 2, v63
	v_and_or_b32 v81, v81, s26, v80
	s_lshl_b32 s20, s20, 13
	v_and_b32_e32 v63, 32, v63
	v_lshlrev_b32_e32 v56, 2, v56
	v_bitop3_b32 v63, v81, s20, v63 bitop3:0xde
	v_lshl_or_b32 v80, v142, 6, v80
	s_lshl_b32 s20, s19, 12
	v_and_b32_e32 v56, 32, v56
	s_add_i32 m0, s22, 0x18000
	v_lshl_add_u64 v[30:31], v[30:31], 0, s[88:89]
	v_bitop3_b32 v144, v80, s20, v56 bitop3:0xde
	s_waitcnt vmcnt(2)
	s_barrier
	global_load_lds_dwordx4 v[30:31], off
	v_lshl_add_u64 v[28:29], v[28:29], 0, s[88:89]
	s_add_i32 m0, s22, 0x1a000
	s_add_i32 s20, s22, 0x8000
	global_load_lds_dwordx4 v[28:29], off
	v_lshl_add_u64 v[26:27], v[26:27], 0, s[88:89]
	s_mov_b32 m0, s20
	s_add_i32 s26, s22, 0xa000
	global_load_lds_dwordx4 v[26:27], off
	v_lshl_add_u64 v[24:25], v[24:25], 0, s[88:89]
	s_mov_b32 m0, s26
	v_readlane_b32 s28, v253, 27
	global_load_lds_dwordx4 v[24:25], off
	v_lshlrev_b32_e32 v24, 14, v57
	v_readlane_b32 s29, v253, 28
	s_add_u32 s27, s4, s28
	v_and_b32_e32 v24, 0xffff8000, v24
	s_addc_u32 s28, s5, s29
	v_readlane_b32 s29, v253, 26
	v_lshl_add_u32 v24, v58, 11, v24
	v_and_b32_e32 v25, 1, v57
	s_add_u32 s4, s4, s29
	v_readlane_b32 s29, v253, 29
	v_lshl_or_b32 v24, v25, 6, v24
	s_addc_u32 s5, s5, s29
	v_lshl_add_u32 v24, v59, 1, v24
	v_mov_b32_e32 v25, v137
	v_lshl_add_u64 v[134:135], s[4:5], 0, v[24:25]
	v_lshlrev_b32_e32 v24, 14, v60
	v_and_b32_e32 v24, 0xffff8000, v24
	v_lshl_add_u32 v24, v61, 11, v24
	v_and_b32_e32 v25, 1, v60
	v_lshl_or_b32 v24, v25, 6, v24
	v_lshl_add_u32 v24, v62, 1, v24
	v_mov_b32_e32 v25, v137
	v_lshl_add_u64 v[140:141], s[4:5], 0, v[24:25]
	v_readlane_b32 s4, v253, 31
	s_add_u32 s2, s2, s4
	v_readlane_b32 s4, v253, 32
	s_waitcnt vmcnt(4)
	s_addc_u32 s3, s3, s4
	s_add_u32 s14, s2, s14
	v_mov_b32_e32 v80, 0
	s_addc_u32 s15, s3, s15
	s_mov_b32 s29, -2
	s_mov_b64 s[2:3], 0
	s_mov_b32 s2, s101
	v_add_u32_e32 v145, 0, v63
	v_mov_b32_e32 v81, v80
	v_mov_b32_e32 v82, v80
	v_mov_b32_e32 v83, v80
	v_mov_b32_e32 v84, v80
	v_mov_b32_e32 v85, v80
	v_mov_b32_e32 v86, v80
	v_mov_b32_e32 v87, v80
	v_mov_b32_e32 v88, v80
	v_mov_b32_e32 v89, v80
	v_mov_b32_e32 v90, v80
	v_mov_b32_e32 v91, v80
	v_mov_b32_e32 v92, v80
	v_mov_b32_e32 v93, v80
	v_mov_b32_e32 v94, v80
	v_mov_b32_e32 v95, v80
	v_mov_b32_e32 v96, v80
	v_mov_b32_e32 v97, v80
	v_mov_b32_e32 v98, v80
	v_mov_b32_e32 v99, v80
	v_mov_b32_e32 v100, v80
	v_mov_b32_e32 v101, v80
	v_mov_b32_e32 v102, v80
	v_mov_b32_e32 v103, v80
	v_mov_b32_e32 v104, v80
	v_mov_b32_e32 v105, v80
	v_mov_b32_e32 v106, v80
	v_mov_b32_e32 v107, v80
	v_mov_b32_e32 v108, v80
	v_mov_b32_e32 v109, v80
	v_mov_b32_e32 v110, v80
	v_mov_b32_e32 v111, v80
	v_mov_b32_e32 v112, v80
	v_mov_b32_e32 v113, v80
	v_mov_b32_e32 v114, v80
	v_mov_b32_e32 v115, v80
	v_mov_b32_e32 v116, v80
	v_mov_b32_e32 v117, v80
	v_mov_b32_e32 v118, v80
	v_mov_b32_e32 v119, v80
	v_mov_b32_e32 v56, v80
	v_mov_b32_e32 v57, v80
	v_mov_b32_e32 v58, v80
	v_mov_b32_e32 v59, v80
	v_mov_b32_e32 v60, v80
	v_mov_b32_e32 v61, v80
	v_mov_b32_e32 v62, v80
	v_mov_b32_e32 v63, v80
	v_mov_b32_e32 v28, v80
	v_mov_b32_e32 v29, v80
	v_mov_b32_e32 v30, v80
	v_mov_b32_e32 v31, v80
	v_mov_b32_e32 v24, v80
	v_mov_b32_e32 v25, v80
	v_mov_b32_e32 v26, v80
	v_mov_b32_e32 v27, v80
	v_mov_b32_e32 v120, v80
	v_mov_b32_e32 v121, v80
	v_mov_b32_e32 v122, v80
	v_mov_b32_e32 v123, v80
	v_mov_b32_e32 v124, v80
	v_mov_b32_e32 v125, v80
	v_mov_b32_e32 v126, v80
	v_mov_b32_e32 v127, v80
.Lmy_pw2_poll:
	s_load_dwordx2 vcc, s[74:75], 0xf8
	s_waitcnt lgkmcnt(0)
	s_add_u32 vcc_lo, vcc_lo, s100
	s_addc_u32 vcc_hi, vcc_hi, 0
	s_add_u32 vcc_lo, vcc_lo, 0x1400
	s_addc_u32 vcc_hi, vcc_hi, 0
	global_load_dword v138, v137, vcc sc1
	s_waitcnt vmcnt(0)
	v_readfirstlane_b32 vcc_lo, v138
	s_and_b32 vcc_hi, vcc_lo, 0xff
	s_cmp_gt_u32 vcc_hi, 7
	s_cbranch_scc1 .Lmy_pw2_ok
	s_sleep 1
	s_branch .Lmy_pw2_poll
.Lmy_pw2_ok:
	s_getreg_b32 m0, hwreg(HW_REG_XCC_ID, 0, 4)
	s_bfe_u32 vcc_hi, vcc_lo, 0x80008
	s_lshr_b32 vcc_lo, vcc_lo, 16
	s_mul_i32 vcc_hi, vcc_hi, m0
	s_lshl_b32 vcc_hi, vcc_hi, 1
	s_mul_i32 m0, m0, m0
	s_lshl_b32 m0, m0, 3
	s_add_u32 vcc_lo, vcc_lo, m0
	s_cmp_eq_u32 vcc_lo, vcc_hi
	s_cbranch_scc1 .Lmy_pw2_l1
	s_mov_b32 s100, 0
	buffer_inv sc1
	s_branch .Lmy_pw2_w
.Lmy_pw2_l1:
	s_mov_b32 s100, 1
	buffer_inv sc0

.LBB0_1030:
	s_add_u32 s4, s27, s2
	s_addc_u32 s5, s28, s3
	s_add_u32 s4, s4, 0xd100100
	s_addc_u32 s5, s5, 0
	s_add_u32 s30, s14, s2
	s_addc_u32 s31, s15, s3
	s_cmpk_eq_i32 s2, 0x700
	s_cselect_b32 s34, 0x800, 0
	s_sub_u32 s4, s4, s34
	s_subb_u32 s5, s5, 0
	s_sub_u32 s30, s30, s34
	s_subb_u32 s31, s31, 0
	s_cmp_eq_u32 s29, 12
	s_cselect_b32 s5, s7, s5
	s_cselect_b32 s4, s6, s4
	s_cselect_b32 s31, s13, s31
	s_cselect_b32 s30, s12, s30
	s_add_i32 s34, 0, 0x10000
	v_add_u32_e32 v138, s34, v144
	ds_read_b128 v[146:149], v138 offset:3072
	ds_read_b128 v[150:153], v138 offset:2048
	ds_read_b128 v[154:157], v138 offset:1024
	ds_read_b128 v[158:161], v138
	v_lshl_add_u64 v[138:139], v[134:135], 0, s[2:3]
	s_add_i32 m0, s22, 0xc000
	ds_read_b128 v[162:165], v145
	ds_read_b128 v[166:169], v145 offset:1024
	ds_read_b128 v[170:173], v145 offset:2048
	ds_read_b128 v[178:181], v145 offset:3072
	ds_read_b128 v[184:187], v145 offset:4096
	ds_read_b128 v[194:197], v145 offset:5120
	ds_read_b128 v[198:201], v145 offset:6144
	ds_read_b128 v[202:205], v145 offset:7168
	global_load_lds_dwordx4 v[138:139], off
	v_lshl_add_u64 v[138:139], v[140:141], 0, s[2:3]
	s_add_i32 m0, s22, 0xe000
	s_nop 0
	global_load_lds_dwordx4 v[138:139], off
	s_waitcnt vmcnt(6)
	s_waitcnt lgkmcnt(0)
	s_barrier
	s_setprio 1
	s_waitcnt lgkmcnt(0)
	v_mfma_f32_16x16x32_bf16 v[124:127], v[158:161], v[162:165], v[124:127]
	v_mfma_f32_16x16x32_bf16 v[120:123], v[150:153], v[162:165], v[120:123]
	v_mfma_f32_16x16x32_bf16 v[24:27], v[158:161], v[170:173], v[24:27]
	v_mfma_f32_16x16x32_bf16 v[28:31], v[150:153], v[170:173], v[28:31]
	v_mfma_f32_16x16x32_bf16 v[60:63], v[158:161], v[184:187], v[60:63]
	v_mfma_f32_16x16x32_bf16 v[56:59], v[150:153], v[184:187], v[56:59]
	v_mfma_f32_16x16x32_bf16 v[116:119], v[158:161], v[198:201], v[116:119]
	v_mfma_f32_16x16x32_bf16 v[112:115], v[150:153], v[198:201], v[112:115]
	v_mfma_f32_16x16x32_bf16 v[124:127], v[154:157], v[166:169], v[124:127]
	v_mfma_f32_16x16x32_bf16 v[120:123], v[146:149], v[166:169], v[120:123]
	v_mfma_f32_16x16x32_bf16 v[24:27], v[154:157], v[178:181], v[24:27]
	v_mfma_f32_16x16x32_bf16 v[28:31], v[146:149], v[178:181], v[28:31]
	v_mfma_f32_16x16x32_bf16 v[60:63], v[154:157], v[194:197], v[60:63]
	v_mfma_f32_16x16x32_bf16 v[56:59], v[146:149], v[194:197], v[56:59]
	v_mfma_f32_16x16x32_bf16 v[116:119], v[154:157], v[202:205], v[116:119]
	v_mfma_f32_16x16x32_bf16 v[112:115], v[146:149], v[202:205], v[112:115]
	s_setprio 0
	s_barrier
	s_add_i32 s34, s34, s21
	v_lshl_add_u64 v[138:139], s[30:31], 0, v[136:137]
	s_mov_b32 m0, s34
	ds_read_b128 v[162:165], v145 offset:16384
	ds_read_b128 v[166:169], v145 offset:17408
	ds_read_b128 v[170:173], v145 offset:18432
	ds_read_b128 v[178:181], v145 offset:19456
	ds_read_b128 v[184:187], v145 offset:20480
	ds_read_b128 v[194:197], v145 offset:21504
	ds_read_b128 v[198:201], v145 offset:22528
	ds_read_b128 v[202:205], v145 offset:23552
	global_load_lds_dwordx4 v[138:139], off
	v_lshl_add_u64 v[174:175], s[30:31], 0, v[132:133]
	s_add_i32 m0, s34, 0x2000
	v_lshl_add_u64 v[182:183], s[4:5], 0, v[128:129]
	global_load_lds_dwordx4 v[174:175], off
	s_mov_b32 m0, s22
	v_lshl_add_u64 v[188:189], s[4:5], 0, v[130:131]
	global_load_lds_dwordx4 v[182:183], off
	s_mov_b32 m0, s23
	s_nop 0
	global_load_lds_dwordx4 v[188:189], off
	s_waitcnt vmcnt(6)
	s_waitcnt lgkmcnt(0)
	s_barrier
	s_setprio 1
	s_waitcnt lgkmcnt(0)
	v_mfma_f32_16x16x32_bf16 v[108:111], v[158:161], v[162:165], v[108:111]
	v_mfma_f32_16x16x32_bf16 v[104:107], v[150:153], v[162:165], v[104:107]
	v_mfma_f32_16x16x32_bf16 v[100:103], v[158:161], v[170:173], v[100:103]
	v_mfma_f32_16x16x32_bf16 v[96:99], v[150:153], v[170:173], v[96:99]
	v_mfma_f32_16x16x32_bf16 v[92:95], v[158:161], v[184:187], v[92:95]
	v_mfma_f32_16x16x32_bf16 v[88:91], v[150:153], v[184:187], v[88:91]
	v_mfma_f32_16x16x32_bf16 v[84:87], v[158:161], v[198:201], v[84:87]
	v_mfma_f32_16x16x32_bf16 v[80:83], v[150:153], v[198:201], v[80:83]
	v_mfma_f32_16x16x32_bf16 v[108:111], v[154:157], v[166:169], v[108:111]
	v_mfma_f32_16x16x32_bf16 v[104:107], v[146:149], v[166:169], v[104:107]
	v_mfma_f32_16x16x32_bf16 v[100:103], v[154:157], v[178:181], v[100:103]
	v_mfma_f32_16x16x32_bf16 v[96:99], v[146:149], v[178:181], v[96:99]
	v_mfma_f32_16x16x32_bf16 v[92:95], v[154:157], v[194:197], v[92:95]
	v_mfma_f32_16x16x32_bf16 v[88:91], v[146:149], v[194:197], v[88:91]
	v_mfma_f32_16x16x32_bf16 v[84:87], v[154:157], v[202:205], v[84:87]
	v_mfma_f32_16x16x32_bf16 v[80:83], v[146:149], v[202:205], v[80:83]
	s_setprio 0
	s_barrier
	s_add_i32 s30, 0, 0x18000
	v_add_u32_e32 v158, s30, v144
	ds_read_b128 v[146:149], v158
	ds_read_b128 v[150:153], v158 offset:1024
	ds_read_b128 v[154:157], v158 offset:2048
	ds_read_b128 v[158:161], v158 offset:3072
	s_add_u32 s4, s4, 0x40000
	s_addc_u32 s5, s5, 0
	s_mov_b32 m0, s24
	v_lshl_add_u64 v[206:207], s[4:5], 0, v[128:129]
	ds_read_b128 v[162:165], v145 offset:32768
	ds_read_b128 v[166:169], v145 offset:33792
	ds_read_b128 v[170:173], v145 offset:34816
	ds_read_b128 v[178:181], v145 offset:35840
	ds_read_b128 v[184:187], v145 offset:36864
	ds_read_b128 v[194:197], v145 offset:37888
	ds_read_b128 v[198:201], v145 offset:38912
	ds_read_b128 v[202:205], v145 offset:39936
	global_load_lds_dwordx4 v[206:207], off
	v_lshl_add_u64 v[206:207], s[4:5], 0, v[130:131]
	s_mov_b32 m0, s25
	s_nop 0
	global_load_lds_dwordx4 v[206:207], off
	s_waitcnt vmcnt(6)
	s_waitcnt lgkmcnt(0)
	s_barrier
	s_setprio 1
	s_waitcnt lgkmcnt(0)
	v_mfma_f32_16x16x32_bf16 v[124:127], v[146:149], v[162:165], v[124:127]
	v_mfma_f32_16x16x32_bf16 v[120:123], v[154:157], v[162:165], v[120:123]
	v_mfma_f32_16x16x32_bf16 v[24:27], v[146:149], v[170:173], v[24:27]
	v_mfma_f32_16x16x32_bf16 v[28:31], v[154:157], v[170:173], v[28:31]
	v_mfma_f32_16x16x32_bf16 v[60:63], v[146:149], v[184:187], v[60:63]
	v_mfma_f32_16x16x32_bf16 v[56:59], v[154:157], v[184:187], v[56:59]
	v_mfma_f32_16x16x32_bf16 v[116:119], v[146:149], v[198:201], v[116:119]
	v_mfma_f32_16x16x32_bf16 v[112:115], v[154:157], v[198:201], v[112:115]
	v_mfma_f32_16x16x32_bf16 v[124:127], v[150:153], v[166:169], v[124:127]
	v_mfma_f32_16x16x32_bf16 v[120:123], v[158:161], v[166:169], v[120:123]
	v_mfma_f32_16x16x32_bf16 v[24:27], v[150:153], v[178:181], v[24:27]
	v_mfma_f32_16x16x32_bf16 v[28:31], v[158:161], v[178:181], v[28:31]
	v_mfma_f32_16x16x32_bf16 v[60:63], v[150:153], v[194:197], v[60:63]
	v_mfma_f32_16x16x32_bf16 v[56:59], v[158:161], v[194:197], v[56:59]
	v_mfma_f32_16x16x32_bf16 v[116:119], v[150:153], v[202:205], v[116:119]
	v_mfma_f32_16x16x32_bf16 v[112:115], v[158:161], v[202:205], v[112:115]
	s_setprio 0
	s_barrier
	s_add_i32 s4, s30, s21
	v_lshl_add_u64 v[138:139], v[138:139], 0, s[88:89]
	s_mov_b32 m0, s4
	ds_read_b128 v[162:165], v145 offset:49152
	ds_read_b128 v[166:169], v145 offset:50176
	ds_read_b128 v[170:173], v145 offset:51200
	ds_read_b128 v[178:181], v145 offset:52224
	ds_read_b128 v[184:187], v145 offset:53248
	ds_read_b128 v[194:197], v145 offset:54272
	ds_read_b128 v[198:201], v145 offset:55296
	ds_read_b128 v[202:205], v145 offset:56320
	global_load_lds_dwordx4 v[138:139], off
	v_lshl_add_u64 v[138:139], v[174:175], 0, s[88:89]
	s_add_i32 m0, s4, 0x2000
	s_nop 0
	global_load_lds_dwordx4 v[138:139], off
	v_lshl_add_u64 v[138:139], v[182:183], 0, s[88:89]
	s_mov_b32 m0, s20
	s_nop 0
	global_load_lds_dwordx4 v[138:139], off
	v_lshl_add_u64 v[138:139], v[188:189], 0, s[88:89]
	s_mov_b32 m0, s26
	s_nop 0
	global_load_lds_dwordx4 v[138:139], off
	s_waitcnt vmcnt(6)
	s_waitcnt lgkmcnt(0)
	s_barrier
	s_setprio 1
	s_waitcnt lgkmcnt(0)
	v_mfma_f32_16x16x32_bf16 v[108:111], v[146:149], v[162:165], v[108:111]
	v_mfma_f32_16x16x32_bf16 v[104:107], v[154:157], v[162:165], v[104:107]
	v_mfma_f32_16x16x32_bf16 v[100:103], v[146:149], v[170:173], v[100:103]
	v_mfma_f32_16x16x32_bf16 v[96:99], v[154:157], v[170:173], v[96:99]
	v_mfma_f32_16x16x32_bf16 v[92:95], v[146:149], v[184:187], v[92:95]
	v_mfma_f32_16x16x32_bf16 v[88:91], v[154:157], v[184:187], v[88:91]
	v_mfma_f32_16x16x32_bf16 v[84:87], v[146:149], v[198:201], v[84:87]
	v_mfma_f32_16x16x32_bf16 v[80:83], v[154:157], v[198:201], v[80:83]
	v_mfma_f32_16x16x32_bf16 v[108:111], v[150:153], v[166:169], v[108:111]
	v_mfma_f32_16x16x32_bf16 v[104:107], v[158:161], v[166:169], v[104:107]
	v_mfma_f32_16x16x32_bf16 v[100:103], v[150:153], v[178:181], v[100:103]
	v_mfma_f32_16x16x32_bf16 v[96:99], v[158:161], v[178:181], v[96:99]
	v_mfma_f32_16x16x32_bf16 v[92:95], v[150:153], v[194:197], v[92:95]
	v_mfma_f32_16x16x32_bf16 v[88:91], v[158:161], v[194:197], v[88:91]
	v_mfma_f32_16x16x32_bf16 v[84:87], v[150:153], v[202:205], v[84:87]
	v_mfma_f32_16x16x32_bf16 v[80:83], v[158:161], v[202:205], v[80:83]
	s_setprio 0
	s_barrier
	s_add_i32 s29, s29, 2
	s_add_u32 s2, s2, 0x100
	s_and_b32 s2, s2, 0x7ff
	s_cmp_gt_u32 s29, 13
	s_cbranch_scc0 .LBB0_1030
	s_nop 0
	s_nop 0
	s_nop 0
	s_cmpk_lt_u32 s17, 0x100
	s_cbranch_scc0 .LBB0_1033
	s_barrier

.LBB0_1051:
	s_ashr_i32 s5, s4, 31
	s_lshl_b64 s[6:7], s[40:41], 18
	v_lshl_add_u32 v64, s3, 6, v136
	s_add_u32 s3, s10, s6
	s_addc_u32 s6, s11, s7
	s_lshl_b64 s[4:5], s[4:5], 5
	s_add_u32 s3, s3, s4
	s_addc_u32 s4, s6, s5
	s_add_u32 s44, s3, 0xf500000
	s_movk_i32 s3, 0x100
	s_addc_u32 s45, s4, 0
	v_cmp_gt_i32_e64 s[6:7], s3, v64
	s_waitcnt lgkmcnt(0)
	s_barrier
	s_and_saveexec_b64 s[4:5], s[6:7]
	s_cbranch_execz .LBB0_1053
	v_lshl_add_u32 v65, v64, 4, 0
	v_add_u32_e32 v65, 0x20800, v65
	ds_read_b128 v[66:69], v65
	v_ashrrev_i32_e32 v65, 31, v64
	v_lshlrev_b64 v[70:71], 5, v[64:65]
	v_lshl_add_u64 v[70:71], s[44:45], 0, v[70:71]
	s_ashr_i32 s3, s2, 31
	s_waitcnt lgkmcnt(0)
	v_mov_b32_e32 v72, v67
	v_mov_b32_e32 v73, v68
	v_mov_b32_e32 v67, v69
	v_pk_add_f32 v[66:67], v[72:73], v[66:67]
	v_lshl_add_u64 v[70:71], s[2:3], 2, v[70:71]
	v_pk_add_f32 v[66:67], v[66:67], v[66:67] op_sel:[0,1] op_sel_hi:[1,0]
	s_cmp_lg_u32 s100, 0
	s_cbranch_scc1 .Lmy_rs_a
	global_store_dword v[70:71], v66, off sc1
	s_branch .Lmy_rs_b
.Lmy_rs_a:
	global_store_dword v[70:71], v66, off
.Lmy_rs_b:
.LBB0_1053:
	s_or_b64 exec, exec, s[4:5]
	s_waitcnt vmcnt(0)
	v_cmp_eq_u32_e32 vcc, 0, v64
	s_barrier
	s_and_saveexec_b64 s[2:3], vcc
	s_cbranch_execz .LBB0_1067
	s_lshl_b32 s4, s14, 4
	s_add_i32 s4, s4, s68
	s_ashr_i32 s5, s4, 31
	s_lshl_b64 s[4:5], s[4:5], 2
	s_mov_b64 s[12:13], exec
	s_add_u32 s4, s10, s4
	s_addc_u32 s5, s11, s5
	v_mbcnt_lo_u32_b32 v65, s12, 0
	s_add_u32 s4, s4, 0xa000
	v_mbcnt_hi_u32_b32 v65, s13, v65
	s_addc_u32 s5, s5, 0
	v_cmp_eq_u32_e32 vcc, 0, v65
	s_and_saveexec_b64 s[14:15], vcc
	s_cbranch_execz .LBB0_1056
	s_bcnt1_i32_b64 s12, s[12:13]
	v_mov_b32_e32 v65, s12
	global_atomic_add v137, v65, s[4:5]

.LBB0_1067:
	s_or_b64 exec, exec, s[2:3]
	s_barrier
	s_and_saveexec_b64 s[2:3], s[6:7]
	s_cbranch_execz .LBB0_1069
	v_readlane_b32 s4, v253, 34
	v_readlane_b32 s7, v253, 37
	s_and_b32 s45, s45, 0xffff
	s_mov_b32 s47, s7
	v_lshlrev_b32_e32 v65, 5, v64
	s_cmp_lg_u32 s100, 0
	s_cbranch_scc1 .Lmy_rl_a
	buffer_load_dwordx4 v[66:69], v65, s[44:47], 0 offen sc1
	buffer_load_dwordx4 v[70:73], v65, s[44:47], 0 offen offset:16 sc1
	s_branch .Lmy_rl_b
.Lmy_rl_a:
	buffer_load_dwordx4 v[66:69], v65, s[44:47], 0 offen sc0
	buffer_load_dwordx4 v[70:73], v65, s[44:47], 0 offen offset:16 sc0
.Lmy_rl_b:
	s_mov_b32 s4, 0xf800000
	v_readlane_b32 s6, v253, 36
	v_readlane_b32 s5, v253, 35
	v_lshl_add_u32 v64, v64, 2, 0
	v_add_u32_e32 v64, 0x21800, v64
	s_waitcnt vmcnt(1)
	v_mov_b32_e32 v74, v67
	v_mov_b32_e32 v75, v68
	v_mov_b32_e32 v67, v69
	v_pk_add_f32 v[66:67], v[74:75], v[66:67]
	s_waitcnt vmcnt(0)
	v_mov_b32_e32 v68, v72
	v_mov_b32_e32 v69, v70
	v_mov_b32_e32 v70, v73
	v_pk_add_f32 v[68:69], v[68:69], v[70:71]
	v_add_f32_e32 v65, v66, v67
	v_add_f32_e32 v65, v65, v69
	v_add_f32_e32 v65, v68, v65
	v_fmamk_f32 v65, v65, 0x3a800000, v190
	v_cmp_gt_f32_e32 vcc, s4, v65
	v_mul_f32_e32 v66, 0x4f800000, v65
	s_nop 0
	v_cndmask_b32_e32 v65, v65, v66, vcc
	v_sqrt_f32_e32 v66, v65
	s_nop 0
	v_add_u32_e32 v67, -1, v66
	v_fma_f32 v68, -v67, v66, v65
	v_cmp_ge_f32_e64 s[6:7], 0, v68
	v_add_u32_e32 v68, 1, v66
	s_nop 0
	v_cndmask_b32_e64 v67, v66, v67, s[6:7]
	v_fma_f32 v66, -v68, v66, v65
	v_cmp_lt_f32_e64 s[6:7], 0, v66
	s_nop 1
	v_cndmask_b32_e64 v66, v67, v68, s[6:7]
	v_mul_f32_e32 v67, 0x37800000, v66
	v_cndmask_b32_e32 v66, v66, v67, vcc
	v_cmp_class_f32_e32 vcc, v65, v192
	s_nop 1
	v_cndmask_b32_e32 v65, v66, v65, vcc
	v_div_scale_f32 v66, s[4:5], v65, v65, 1.0
	v_rcp_f32_e32 v67, v66
	s_nop 0
	v_fma_f32 v68, -v66, v67, 1.0
	v_fmac_f32_e32 v67, v68, v67
	v_div_scale_f32 v68, vcc, 1.0, v65, 1.0
	v_mul_f32_e32 v69, v68, v67
	v_fma_f32 v70, -v66, v69, v68
	v_fmac_f32_e32 v69, v70, v67
	v_fma_f32 v66, -v66, v69, v68
	v_div_fmas_f32 v66, v66, v67, v69
	v_div_fixup_f32 v65, v66, v65, 1.0
	ds_write_b32 v64, v65
